# attention: same move (last P.V MFMAs behind the barrier, interleaved with DMA issue) at the second per-tile barrier too
# baseline (speedup 1.0000x reference)
.LBB0_1035:
	v_exp_f32_e32 v218, v88
	v_exp_f32_e32 v225, v89
	s_add_i32 s0, s75, 1
	s_cmp_lg_u32 s75, 2
	s_cselect_b32 s76, s0, 0
	v_exp_f32_e32 v120, v80
	v_exp_f32_e32 v121, v81
	v_exp_f32_e32 v122, v82
	v_exp_f32_e32 v123, v83
	v_exp_f32_e32 v124, v84
	v_exp_f32_e32 v125, v85
	v_exp_f32_e32 v126, v86
	v_exp_f32_e32 v127, v87
	v_exp_f32_e32 v226, v90
	v_exp_f32_e32 v227, v91
	v_exp_f32_e32 v228, v92
	v_exp_f32_e32 v229, v93
	v_exp_f32_e32 v230, v94
	v_exp_f32_e32 v231, v95
	s_setprio 1
	v_lshl_add_u32 v223, s76, 13, v190
	v_add_u32_e32 v68, v223, v191
	ds_read_b128 v[64:67], v68 offset:49152
	ds_read_b128 v[68:71], v68 offset:53248
	v_add_u32_e32 v116, v223, v192
	ds_read_b128 v[112:115], v116 offset:49152
	ds_read_b128 v[116:119], v116 offset:53248
	s_waitcnt lgkmcnt(0)
	v_mfma_f32_32x32x16_bf16 v[80:95], v[64:67], v[108:111], 0
	v_mfma_f32_32x32x16_bf16 v[64:79], v[68:71], v[108:111], 0
	v_mfma_f32_32x32x16_bf16 v[80:95], v[112:115], v[104:107], v[80:95]
	v_mfma_f32_32x32x16_bf16 v[64:79], v[116:119], v[104:107], v[64:79]
	v_add_u32_e32 v116, v223, v193
	ds_read_b128 v[112:115], v116 offset:49152
	ds_read_b128 v[116:119], v116 offset:53248
	s_waitcnt lgkmcnt(0)
	v_mfma_f32_32x32x16_bf16 v[80:95], v[112:115], v[100:103], v[80:95]
	v_mfma_f32_32x32x16_bf16 v[64:79], v[116:119], v[100:103], v[64:79]
	v_add_u32_e32 v116, v223, v194
	ds_read_b128 v[112:115], v116 offset:49152
	ds_read_b128 v[116:119], v116 offset:53248
	s_waitcnt lgkmcnt(0)
	v_mfma_f32_32x32x16_bf16 v[80:95], v[112:115], v[96:99], v[80:95]
	v_mfma_f32_32x32x16_bf16 v[64:79], v[116:119], v[96:99], v[64:79]
	s_setprio 0
	v_exp_f32_e32 v160, v160
	v_exp_f32_e32 v161, v161
	v_add_f32_e32 v112, v120, v160
	v_add_f32_e32 v113, v121, v161
	v_exp_f32_e32 v162, v162
	v_add_f32_e32 v112, v112, v122
	v_add_f32_e32 v113, v113, v123
	v_exp_f32_e32 v163, v163
	v_add_f32_e32 v112, v112, v162
	v_add_f32_e32 v113, v113, v163
	v_exp_f32_e32 v164, v164
	v_add_f32_e32 v112, v112, v124
	v_add_f32_e32 v113, v113, v125
	v_exp_f32_e32 v165, v165
	v_add_f32_e32 v112, v112, v164
	v_add_f32_e32 v113, v113, v165
	v_exp_f32_e32 v166, v166
	v_add_f32_e32 v112, v112, v126
	v_add_f32_e32 v113, v113, v127
	v_exp_f32_e32 v167, v167
	v_add_f32_e32 v112, v112, v166
	v_add_f32_e32 v113, v113, v167
	v_exp_f32_e32 v168, v168
	v_add_f32_e32 v112, v112, v218
	v_add_f32_e32 v113, v113, v225
	v_exp_f32_e32 v169, v169
	v_add_f32_e32 v112, v112, v168
	v_add_f32_e32 v113, v113, v169
	v_exp_f32_e32 v170, v170
	v_add_f32_e32 v112, v112, v226
	v_add_f32_e32 v113, v113, v227
	v_exp_f32_e32 v171, v171
	v_add_f32_e32 v112, v112, v170
	v_add_f32_e32 v113, v113, v171
	v_exp_f32_e32 v172, v172
	v_add_f32_e32 v112, v112, v228
	v_add_f32_e32 v113, v113, v229
	v_exp_f32_e32 v173, v173
	v_exp_f32_e32 v174, v174
	v_exp_f32_e32 v175, v175
	v_add_f32_e32 v112, v112, v172
	v_add_f32_e32 v113, v113, v173
	s_nop 0
	v_add_f32_e32 v112, v112, v230
	v_add_f32_e32 v113, v113, v231
	s_nop 0
	v_add_f32_e32 v112, v112, v174
	v_add_f32_e32 v113, v113, v175
	s_nop 0
	v_add_f32_e32 v223, v112, v113
	v_cvt_pk_bf16_f32 v112, v120, v121
	v_cvt_pk_bf16_f32 v113, v122, v123
	v_cvt_pk_bf16_f32 v114, v124, v125
	v_cvt_pk_bf16_f32 v115, v126, v127
	v_cvt_pk_bf16_f32 v116, v218, v225
	s_nop 0
	v_mov_b32_e32 v224, v223
	s_nop 1
	v_permlane32_swap_b32_e32 v223, v224
	v_cvt_pk_bf16_f32 v117, v226, v227
	v_cvt_pk_bf16_f32 v118, v228, v229
	v_cvt_pk_bf16_f32 v119, v230, v231
	v_cvt_pk_bf16_f32 v120, v160, v161
	v_cvt_pk_bf16_f32 v121, v162, v163
	v_cvt_pk_bf16_f32 v122, v164, v165
	v_cvt_pk_bf16_f32 v123, v166, v167
	v_cvt_pk_bf16_f32 v124, v168, v169
	v_cvt_pk_bf16_f32 v125, v170, v171
	v_cvt_pk_bf16_f32 v126, v172, v173
	v_cvt_pk_bf16_f32 v127, v174, v175
	v_permlane32_swap_b32_e32 v112, v114
	v_permlane32_swap_b32_e32 v113, v115
	v_permlane32_swap_b32_e32 v116, v118
	v_permlane32_swap_b32_e32 v117, v119
	v_permlane32_swap_b32_e32 v120, v122
	v_permlane32_swap_b32_e32 v121, v123
	v_permlane32_swap_b32_e32 v124, v126
	v_permlane32_swap_b32_e32 v125, v127
	s_lshl_b32 s75, s75, 14
	v_add_u32_e32 v226, s75, v187
	ds_read_b64_tr_b16 v[160:161], v226 offset:0
	ds_read_b64_tr_b16 v[162:163], v226 offset:0x800
	ds_read_b64_tr_b16 v[164:165], v226 offset:0x1000
	ds_read_b64_tr_b16 v[166:167], v226 offset:0x1800
	ds_read_b64_tr_b16 v[168:169], v226 offset:0x2000
	ds_read_b64_tr_b16 v[170:171], v226 offset:0x2800
	ds_read_b64_tr_b16 v[172:173], v226 offset:0x3000
	ds_read_b64_tr_b16 v[174:175], v226 offset:0x3800
	s_setprio 1
	s_waitcnt lgkmcnt(6)
	v_mfma_f32_32x32x16_bf16 v[48:63], v[112:115], v[160:163], v[48:63]
	s_waitcnt lgkmcnt(4)
	v_mfma_f32_32x32x16_bf16 v[48:63], v[116:119], v[164:167], v[48:63]
	s_waitcnt lgkmcnt(2)
	v_mfma_f32_32x32x16_bf16 v[48:63], v[120:123], v[168:171], v[48:63]
	s_waitcnt lgkmcnt(0)
	v_mfma_f32_32x32x16_bf16 v[48:63], v[124:127], v[172:175], v[48:63]
	s_setprio 0
	v_max3_f32 v160, v80, v81, v82
	v_max3_f32 v161, v64, v65, v66
	v_max_f32_e32 v162, v79, v79
	v_max3_f32 v160, v160, v83, v84
	v_max3_f32 v161, v161, v67, v68
	v_max_f32_e32 v163, v95, v95
	v_max3_f32 v160, v160, v85, v86
	v_max3_f32 v161, v161, v69, v70
	v_max_f32_e32 v162, v163, v162
	v_max3_f32 v160, v160, v87, v88
	v_max3_f32 v161, v161, v71, v72
	s_nop 0
	v_max3_f32 v160, v160, v89, v90
	v_max3_f32 v161, v161, v73, v74
	s_nop 0
	v_max3_f32 v160, v160, v91, v92
	v_max3_f32 v161, v161, v75, v76
	s_nop 0
	v_max3_f32 v160, v160, v93, v94
	v_max3_f32 v161, v161, v77, v78
	s_nop 0
	v_max3_f32 v160, v160, v161, v162
	s_nop 0
	v_mov_b32_e32 v161, v160
	s_nop 1
	v_permlane32_swap_b32_e32 v160, v161
	v_max_f32_e32 v161, v161, v161
	v_max_f32_e32 v160, v160, v160
	v_max_f32_e32 v218, v160, v161
	ds_read_b64_tr_b16 v[160:161], v226 offset:0x200
	ds_read_b64_tr_b16 v[162:163], v226 offset:0xa00
	ds_read_b64_tr_b16 v[164:165], v226 offset:0x1200
	ds_read_b64_tr_b16 v[166:167], v226 offset:0x1a00
	ds_read_b64_tr_b16 v[168:169], v226 offset:0x2200
	ds_read_b64_tr_b16 v[170:171], v226 offset:0x2a00
	ds_read_b64_tr_b16 v[172:173], v226 offset:0x3200
	ds_read_b64_tr_b16 v[174:175], v226 offset:0x3a00
	s_setprio 1
	s_waitcnt lgkmcnt(6)
	v_mfma_f32_32x32x16_bf16 v[32:47], v[112:115], v[160:163], v[32:47]
	s_waitcnt lgkmcnt(4)
	v_mfma_f32_32x32x16_bf16 v[32:47], v[116:119], v[164:167], v[32:47]
	s_waitcnt lgkmcnt(2)
	v_mfma_f32_32x32x16_bf16 v[32:47], v[120:123], v[168:171], v[32:47]
	s_waitcnt lgkmcnt(0)
	v_mfma_f32_32x32x16_bf16 v[32:47], v[124:127], v[172:175], v[32:47]
	s_setprio 0
	v_sub_f32_e32 v160, v218, v222
	v_cmp_ge_f32_e32 vcc, s71, v160
	s_cmp_eq_u64 vcc, exec
	v_max_f32_e32 v160, v222, v222
	v_max_f32_e32 v225, v160, v218
	s_cselect_b64 s[0:1], -1, 0
	v_cndmask_b32_e64 v218, v225, v222, s[0:1]
	v_mul_f32_e32 v161, 0xbe38aa3b, v218
	v_fma_f32 v80, v80, v197, v161
	v_fma_f32 v81, v81, v197, v161
	v_fma_f32 v82, v82, v197, v161
	v_fma_f32 v83, v83, v197, v161
	v_fma_f32 v84, v84, v197, v161
	v_fma_f32 v85, v85, v197, v161
	v_fma_f32 v86, v86, v197, v161
	v_fma_f32 v87, v87, v197, v161
	v_fma_f32 v88, v88, v197, v161
	v_fma_f32 v89, v89, v197, v161
	v_fma_f32 v90, v90, v197, v161
	v_fma_f32 v91, v91, v197, v161
	v_fma_f32 v92, v92, v197, v161
	v_fma_f32 v93, v93, v197, v161
	v_fma_f32 v94, v94, v197, v161
	v_fma_f32 v95, v95, v197, v161
	v_fma_f32 v174, v64, v197, v161
	v_fma_f32 v175, v65, v197, v161
	v_fma_f32 v172, v66, v197, v161
	v_fma_f32 v173, v67, v197, v161
	v_fma_f32 v170, v68, v197, v161
	v_fma_f32 v171, v69, v197, v161
	v_fma_f32 v168, v70, v197, v161
	v_fma_f32 v169, v71, v197, v161
	v_fma_f32 v166, v72, v197, v161
	v_fma_f32 v167, v73, v197, v161
	v_fma_f32 v164, v74, v197, v161
	v_fma_f32 v165, v75, v197, v161
	v_fma_f32 v162, v76, v197, v161
	v_fma_f32 v163, v77, v197, v161
	v_fma_f32 v160, v78, v197, v161
	v_fma_f32 v161, v79, v197, v161
	ds_read_b64_tr_b16 v[64:65], v226 offset:0x400
	ds_read_b64_tr_b16 v[66:67], v226 offset:0xc00
	ds_read_b64_tr_b16 v[68:69], v226 offset:0x1400
	ds_read_b64_tr_b16 v[70:71], v226 offset:0x1c00
	ds_read_b64_tr_b16 v[72:73], v226 offset:0x2400
	ds_read_b64_tr_b16 v[74:75], v226 offset:0x2c00
	ds_read_b64_tr_b16 v[76:77], v226 offset:0x3400
	ds_read_b64_tr_b16 v[78:79], v226 offset:0x3c00
	s_setprio 1
	s_waitcnt lgkmcnt(6)
	v_mfma_f32_32x32x16_bf16 v[16:31], v[112:115], v[64:67], v[16:31]
	s_waitcnt lgkmcnt(4)
	v_mfma_f32_32x32x16_bf16 v[16:31], v[116:119], v[68:71], v[16:31]
	s_waitcnt lgkmcnt(2)
	v_mfma_f32_32x32x16_bf16 v[16:31], v[120:123], v[72:75], v[16:31]
	s_waitcnt lgkmcnt(0)
	v_mfma_f32_32x32x16_bf16 v[16:31], v[124:127], v[76:79], v[16:31]
	s_setprio 0
	ds_read_b64_tr_b16 v[64:65], v226 offset:0x600
	ds_read_b64_tr_b16 v[66:67], v226 offset:0xe00
	ds_read_b64_tr_b16 v[68:69], v226 offset:0x1600
	ds_read_b64_tr_b16 v[70:71], v226 offset:0x1e00
	ds_read_b64_tr_b16 v[72:73], v226 offset:0x2600
	ds_read_b64_tr_b16 v[74:75], v226 offset:0x2e00
	ds_read_b64_tr_b16 v[76:77], v226 offset:0x3600
	ds_read_b64_tr_b16 v[78:79], v226 offset:0x3e00
	s_setprio 0
	s_waitcnt vmcnt(0) lgkmcnt(0)
	s_barrier
	s_cmp_gt_u32 s74, 28
	s_cselect_b64 s[48:49], -1, 0
	s_and_b64 vcc, exec, s[48:49]
	s_cbranch_vccnz .Lpv3_skip_a
	s_add_i32 s77, s77, s33
	s_setprio 1
	v_mfma_f32_32x32x16_bf16 v[0:15], v[112:115], v[64:67], v[0:15]
	s_add_i32 m0, s77, 0xc000
	s_add_i32 s75, s51, s75
	v_lshl_add_u64 v[64:65], v[176:177], 0, s[14:15]
	global_load_lds_dwordx4 v[64:65], off
	v_mfma_f32_32x32x16_bf16 v[0:15], v[116:119], v[68:71], v[0:15]
	v_lshl_add_u64 v[64:65], v[178:179], 0, s[34:35]
	s_mov_b32 m0, s75
	s_nop 0
	global_load_lds_dwordx4 v[64:65], off
	v_mfma_f32_32x32x16_bf16 v[0:15], v[120:123], v[72:75], v[0:15]
	v_lshl_add_u64 v[64:65], v[180:181], 0, s[34:35]
	s_add_i32 m0, s75, 0x2000
	s_nop 0
	global_load_lds_dwordx4 v[64:65], off
	v_mfma_f32_32x32x16_bf16 v[0:15], v[124:127], v[76:79], v[0:15]
	s_setprio 0
	s_branch .LBB0_1037
.Lpv3_skip_a:
	s_setprio 1
	v_mfma_f32_32x32x16_bf16 v[0:15], v[112:115], v[64:67], v[0:15]
	v_mfma_f32_32x32x16_bf16 v[0:15], v[116:119], v[68:71], v[0:15]
	v_mfma_f32_32x32x16_bf16 v[0:15], v[120:123], v[72:75], v[0:15]
	v_mfma_f32_32x32x16_bf16 v[0:15], v[124:127], v[76:79], v[0:15]
	s_setprio 0

.LBB0_1054:
	v_exp_f32_e32 v227, v88
	v_exp_f32_e32 v232, v89
	s_add_i32 s0, s76, 1
	s_cmp_lg_u32 s76, 2
	s_cselect_b32 s36, s0, 0
	v_exp_f32_e32 v120, v80
	v_exp_f32_e32 v121, v81
	v_exp_f32_e32 v122, v82
	v_exp_f32_e32 v123, v83
	v_exp_f32_e32 v124, v84
	v_exp_f32_e32 v125, v85
	v_exp_f32_e32 v126, v86
	v_exp_f32_e32 v127, v87
	v_exp_f32_e32 v233, v90
	v_exp_f32_e32 v234, v91
	v_exp_f32_e32 v235, v92
	v_exp_f32_e32 v236, v93
	v_exp_f32_e32 v237, v94
	v_exp_f32_e32 v238, v95
	s_setprio 1
	v_lshl_add_u32 v230, s36, 13, v190
	v_add_u32_e32 v68, v230, v191
	ds_read_b128 v[64:67], v68 offset:49152
	ds_read_b128 v[68:71], v68 offset:53248
	v_add_u32_e32 v116, v230, v192
	ds_read_b128 v[112:115], v116 offset:49152
	ds_read_b128 v[116:119], v116 offset:53248
	s_waitcnt lgkmcnt(0)
	v_mfma_f32_32x32x16_bf16 v[80:95], v[64:67], v[108:111], 0
	v_mfma_f32_32x32x16_bf16 v[64:79], v[68:71], v[108:111], 0
	v_mfma_f32_32x32x16_bf16 v[80:95], v[112:115], v[104:107], v[80:95]
	v_mfma_f32_32x32x16_bf16 v[64:79], v[116:119], v[104:107], v[64:79]
	v_add_u32_e32 v116, v230, v193
	ds_read_b128 v[112:115], v116 offset:49152
	ds_read_b128 v[116:119], v116 offset:53248
	s_waitcnt lgkmcnt(0)
	v_mfma_f32_32x32x16_bf16 v[80:95], v[112:115], v[100:103], v[80:95]
	v_mfma_f32_32x32x16_bf16 v[64:79], v[116:119], v[100:103], v[64:79]
	v_add_u32_e32 v116, v230, v194
	ds_read_b128 v[112:115], v116 offset:49152
	ds_read_b128 v[116:119], v116 offset:53248
	s_waitcnt lgkmcnt(0)
	v_mfma_f32_32x32x16_bf16 v[80:95], v[112:115], v[96:99], v[80:95]
	v_mfma_f32_32x32x16_bf16 v[64:79], v[116:119], v[96:99], v[64:79]
	s_setprio 0
	v_exp_f32_e32 v166, v166
	v_exp_f32_e32 v167, v167
	v_add_f32_e32 v112, v120, v166
	v_add_f32_e32 v113, v121, v167
	v_exp_f32_e32 v168, v168
	v_add_f32_e32 v112, v112, v122
	v_add_f32_e32 v113, v113, v123
	v_exp_f32_e32 v169, v169
	v_add_f32_e32 v112, v112, v168
	v_add_f32_e32 v113, v113, v169
	v_exp_f32_e32 v170, v170
	v_add_f32_e32 v112, v112, v124
	v_add_f32_e32 v113, v113, v125
	v_exp_f32_e32 v171, v171
	v_add_f32_e32 v112, v112, v170
	v_add_f32_e32 v113, v113, v171
	v_exp_f32_e32 v172, v172
	v_add_f32_e32 v112, v112, v126
	v_add_f32_e32 v113, v113, v127
	v_exp_f32_e32 v173, v173
	v_add_f32_e32 v112, v112, v172
	v_add_f32_e32 v113, v113, v173
	v_exp_f32_e32 v174, v174
	v_add_f32_e32 v112, v112, v227
	v_add_f32_e32 v113, v113, v232
	v_exp_f32_e32 v175, v175
	v_add_f32_e32 v112, v112, v174
	v_add_f32_e32 v113, v113, v175
	v_exp_f32_e32 v176, v176
	v_add_f32_e32 v112, v112, v233
	v_add_f32_e32 v113, v113, v234
	v_exp_f32_e32 v177, v177
	v_add_f32_e32 v112, v112, v176
	v_add_f32_e32 v113, v113, v177
	v_exp_f32_e32 v178, v178
	v_add_f32_e32 v112, v112, v235
	v_add_f32_e32 v113, v113, v236
	v_exp_f32_e32 v179, v179
	v_exp_f32_e32 v180, v180
	v_exp_f32_e32 v181, v181
	v_add_f32_e32 v112, v112, v178
	v_add_f32_e32 v113, v113, v179
	s_nop 0
	v_add_f32_e32 v112, v112, v237
	v_add_f32_e32 v113, v113, v238
	s_nop 0
	v_add_f32_e32 v112, v112, v180
	v_add_f32_e32 v113, v113, v181
	s_nop 0
	v_add_f32_e32 v230, v112, v113
	v_cvt_pk_bf16_f32 v112, v120, v121
	v_cvt_pk_bf16_f32 v113, v122, v123
	v_cvt_pk_bf16_f32 v114, v124, v125
	v_cvt_pk_bf16_f32 v115, v126, v127
	v_cvt_pk_bf16_f32 v116, v227, v232
	s_nop 0
	v_mov_b32_e32 v231, v230
	s_nop 1
	v_permlane32_swap_b32_e32 v230, v231
	v_cvt_pk_bf16_f32 v117, v233, v234
	v_cvt_pk_bf16_f32 v118, v235, v236
	v_cvt_pk_bf16_f32 v119, v237, v238
	v_cvt_pk_bf16_f32 v120, v166, v167
	v_cvt_pk_bf16_f32 v121, v168, v169
	v_cvt_pk_bf16_f32 v122, v170, v171
	v_cvt_pk_bf16_f32 v123, v172, v173
	v_cvt_pk_bf16_f32 v124, v174, v175
	v_cvt_pk_bf16_f32 v125, v176, v177
	v_cvt_pk_bf16_f32 v126, v178, v179
	v_cvt_pk_bf16_f32 v127, v180, v181
	v_permlane32_swap_b32_e32 v112, v114
	v_permlane32_swap_b32_e32 v113, v115
	v_permlane32_swap_b32_e32 v116, v118
	v_permlane32_swap_b32_e32 v117, v119
	v_permlane32_swap_b32_e32 v120, v122
	v_permlane32_swap_b32_e32 v121, v123
	v_permlane32_swap_b32_e32 v124, v126
	v_permlane32_swap_b32_e32 v125, v127
	s_lshl_b32 s41, s76, 14
	v_add_u32_e32 v233, s41, v187
	ds_read_b64_tr_b16 v[166:167], v233 offset:0
	ds_read_b64_tr_b16 v[168:169], v233 offset:0x800
	ds_read_b64_tr_b16 v[170:171], v233 offset:0x1000
	ds_read_b64_tr_b16 v[172:173], v233 offset:0x1800
	ds_read_b64_tr_b16 v[174:175], v233 offset:0x2000
	ds_read_b64_tr_b16 v[176:177], v233 offset:0x2800
	ds_read_b64_tr_b16 v[178:179], v233 offset:0x3000
	ds_read_b64_tr_b16 v[180:181], v233 offset:0x3800
	s_setprio 1
	s_waitcnt lgkmcnt(6)
	v_mfma_f32_32x32x16_bf16 v[48:63], v[112:115], v[166:169], v[48:63]
	s_waitcnt lgkmcnt(4)
	v_mfma_f32_32x32x16_bf16 v[48:63], v[116:119], v[170:173], v[48:63]
	s_waitcnt lgkmcnt(2)
	v_mfma_f32_32x32x16_bf16 v[48:63], v[120:123], v[174:177], v[48:63]
	s_waitcnt lgkmcnt(0)
	v_mfma_f32_32x32x16_bf16 v[48:63], v[124:127], v[178:181], v[48:63]
	s_setprio 0
	v_max3_f32 v166, v80, v81, v82
	v_max3_f32 v167, v64, v65, v66
	v_max_f32_e32 v168, v79, v79
	v_max3_f32 v166, v166, v83, v84
	v_max3_f32 v167, v167, v67, v68
	v_max_f32_e32 v169, v95, v95
	v_max3_f32 v166, v166, v85, v86
	v_max3_f32 v167, v167, v69, v70
	v_max_f32_e32 v168, v169, v168
	v_max3_f32 v166, v166, v87, v88
	v_max3_f32 v167, v167, v71, v72
	s_nop 0
	v_max3_f32 v166, v166, v89, v90
	v_max3_f32 v167, v167, v73, v74
	s_nop 0
	v_max3_f32 v166, v166, v91, v92
	v_max3_f32 v167, v167, v75, v76
	s_nop 0
	v_max3_f32 v166, v166, v93, v94
	v_max3_f32 v167, v167, v77, v78
	s_nop 0
	v_max3_f32 v166, v166, v167, v168
	s_nop 0
	v_mov_b32_e32 v167, v166
	s_nop 1
	v_permlane32_swap_b32_e32 v166, v167
	v_max_f32_e32 v167, v167, v167
	v_max_f32_e32 v166, v166, v166
	v_max_f32_e32 v227, v166, v167
	ds_read_b64_tr_b16 v[166:167], v233 offset:0x200
	ds_read_b64_tr_b16 v[168:169], v233 offset:0xa00
	ds_read_b64_tr_b16 v[170:171], v233 offset:0x1200
	ds_read_b64_tr_b16 v[172:173], v233 offset:0x1a00
	ds_read_b64_tr_b16 v[174:175], v233 offset:0x2200
	ds_read_b64_tr_b16 v[176:177], v233 offset:0x2a00
	ds_read_b64_tr_b16 v[178:179], v233 offset:0x3200
	ds_read_b64_tr_b16 v[180:181], v233 offset:0x3a00
	s_setprio 1
	s_waitcnt lgkmcnt(6)
	v_mfma_f32_32x32x16_bf16 v[32:47], v[112:115], v[166:169], v[32:47]
	s_waitcnt lgkmcnt(4)
	v_mfma_f32_32x32x16_bf16 v[32:47], v[116:119], v[170:173], v[32:47]
	s_waitcnt lgkmcnt(2)
	v_mfma_f32_32x32x16_bf16 v[32:47], v[120:123], v[174:177], v[32:47]
	s_waitcnt lgkmcnt(0)
	v_mfma_f32_32x32x16_bf16 v[32:47], v[124:127], v[178:181], v[32:47]
	s_setprio 0
	v_sub_f32_e32 v166, v227, v229
	v_cmp_ge_f32_e32 vcc, s71, v166
	s_cmp_eq_u64 vcc, exec
	v_max_f32_e32 v166, v229, v229
	v_max_f32_e32 v232, v166, v227
	s_cselect_b64 s[0:1], -1, 0
	v_cndmask_b32_e64 v227, v232, v229, s[0:1]
	v_mul_f32_e32 v167, 0xbe38aa3b, v227
	v_fma_f32 v80, v80, v197, v167
	v_fma_f32 v81, v81, v197, v167
	v_fma_f32 v82, v82, v197, v167
	v_fma_f32 v83, v83, v197, v167
	v_fma_f32 v84, v84, v197, v167
	v_fma_f32 v85, v85, v197, v167
	v_fma_f32 v86, v86, v197, v167
	v_fma_f32 v87, v87, v197, v167
	v_fma_f32 v88, v88, v197, v167
	v_fma_f32 v89, v89, v197, v167
	v_fma_f32 v90, v90, v197, v167
	v_fma_f32 v91, v91, v197, v167
	v_fma_f32 v92, v92, v197, v167
	v_fma_f32 v93, v93, v197, v167
	v_fma_f32 v94, v94, v197, v167
	v_fma_f32 v95, v95, v197, v167
	v_fma_f32 v180, v64, v197, v167
	v_fma_f32 v181, v65, v197, v167
	v_fma_f32 v178, v66, v197, v167
	v_fma_f32 v179, v67, v197, v167
	v_fma_f32 v176, v68, v197, v167
	v_fma_f32 v177, v69, v197, v167
	v_fma_f32 v174, v70, v197, v167
	v_fma_f32 v175, v71, v197, v167
	v_fma_f32 v172, v72, v197, v167
	v_fma_f32 v173, v73, v197, v167
	v_fma_f32 v170, v74, v197, v167
	v_fma_f32 v171, v75, v197, v167
	v_fma_f32 v168, v76, v197, v167
	v_fma_f32 v169, v77, v197, v167
	v_fma_f32 v166, v78, v197, v167
	v_fma_f32 v167, v79, v197, v167
	ds_read_b64_tr_b16 v[64:65], v233 offset:0x400
	ds_read_b64_tr_b16 v[66:67], v233 offset:0xc00
	ds_read_b64_tr_b16 v[68:69], v233 offset:0x1400
	ds_read_b64_tr_b16 v[70:71], v233 offset:0x1c00
	ds_read_b64_tr_b16 v[72:73], v233 offset:0x2400
	ds_read_b64_tr_b16 v[74:75], v233 offset:0x2c00
	ds_read_b64_tr_b16 v[76:77], v233 offset:0x3400
	ds_read_b64_tr_b16 v[78:79], v233 offset:0x3c00
	s_setprio 1
	s_waitcnt lgkmcnt(6)
	v_mfma_f32_32x32x16_bf16 v[16:31], v[112:115], v[64:67], v[16:31]
	s_waitcnt lgkmcnt(4)
	v_mfma_f32_32x32x16_bf16 v[16:31], v[116:119], v[68:71], v[16:31]
	s_waitcnt lgkmcnt(2)
	v_mfma_f32_32x32x16_bf16 v[16:31], v[120:123], v[72:75], v[16:31]
	s_waitcnt lgkmcnt(0)
	v_mfma_f32_32x32x16_bf16 v[16:31], v[124:127], v[76:79], v[16:31]
	s_setprio 0
	ds_read_b64_tr_b16 v[64:65], v233 offset:0x600
	ds_read_b64_tr_b16 v[66:67], v233 offset:0xe00
	ds_read_b64_tr_b16 v[68:69], v233 offset:0x1600
	ds_read_b64_tr_b16 v[70:71], v233 offset:0x1e00
	ds_read_b64_tr_b16 v[72:73], v233 offset:0x2600
	ds_read_b64_tr_b16 v[74:75], v233 offset:0x2e00
	ds_read_b64_tr_b16 v[76:77], v233 offset:0x3600
	ds_read_b64_tr_b16 v[78:79], v233 offset:0x3e00
	s_setprio 0
	s_waitcnt vmcnt(0) lgkmcnt(0)
	s_barrier
	s_cmp_gt_u32 s37, 28
	s_cselect_b64 s[38:39], -1, 0
	s_and_b64 vcc, exec, s[38:39]
	s_cbranch_vccnz .Lpv3_skip_b
	s_add_i32 s40, s40, s74
	s_setprio 1
	v_mfma_f32_32x32x16_bf16 v[0:15], v[112:115], v[64:67], v[0:15]
	s_add_i32 m0, s40, 0xc000
	s_add_i32 s40, s75, s41
	v_lshl_add_u64 v[64:65], v[160:161], 0, s[60:61]
	global_load_lds_dwordx4 v[64:65], off
	v_mfma_f32_32x32x16_bf16 v[0:15], v[116:119], v[68:71], v[0:15]
	v_lshl_add_u64 v[64:65], v[162:163], 0, s[34:35]
	s_mov_b32 m0, s40
	s_nop 0
	global_load_lds_dwordx4 v[64:65], off
	v_mfma_f32_32x32x16_bf16 v[0:15], v[120:123], v[72:75], v[0:15]
	v_lshl_add_u64 v[64:65], v[164:165], 0, s[34:35]
	s_add_i32 m0, s40, 0x2000
	s_nop 0
	global_load_lds_dwordx4 v[64:65], off
	v_mfma_f32_32x32x16_bf16 v[0:15], v[124:127], v[76:79], v[0:15]
	s_setprio 0
	s_branch .LBB0_1056
